# v42 + loop-carried K increments/exit test hoisted from after the loop-back barrier into the last load segment (3 GEMM loops)
# speedup vs baseline: 1.0101x; 1.0011x over previous
.LBB0_164:
	s_add_u32 s24, s18, 0xfff80080
	s_addc_u32 s25, s19, -1
	s_add_i32 s52, 0, 0x10000
	s_cmp_eq_u32 s51, 28
	s_cselect_b32 s47, s9, s25
	s_cselect_b32 s46, s21, s24
	v_add_u32_e32 v6, s52, v172
	s_cselect_b32 s25, s1, s50
	s_cselect_b32 s24, s23, s29
	s_add_i32 s54, 0, 0x14000
	ds_read_b128 v[126:129], v6
	ds_read_b128 v[130:133], v6 offset:1024
	ds_read_b128 v[142:145], v6 offset:2048
	ds_read_b128 v[146:149], v6 offset:3072
	v_add_u32_e32 v6, s54, v172
	ds_read_b128 v[166:169], v6
	ds_read_b128 v[204:207], v6 offset:1024
	ds_read_b128 v[208:211], v6 offset:2048
	ds_read_b128 v[216:219], v6 offset:3072
	v_lshl_add_u64 v[6:7], s[18:19], 0, v[162:163]
	s_add_i32 m0, s79, 0xc000
	ds_read_b128 v[220:223], v198
	ds_read_b128 v[224:227], v198 offset:1024
	ds_read_b128 v[228:231], v198 offset:2048
	ds_read_b128 v[232:235], v198 offset:3072
	ds_read_b128 v[236:239], v198 offset:4096
	ds_read_b128 v[240:243], v198 offset:5120
	ds_read_b128 v[244:247], v198 offset:6144
	ds_read_b128 v[248:251], v198 offset:7168
	global_load_lds_dwordx4 v[6:7], off
	v_lshl_add_u64 v[6:7], s[18:19], 0, v[164:165]
	s_add_i32 m0, s79, 0xe000
	s_nop 0
	global_load_lds_dwordx4 v[6:7], off
	s_waitcnt vmcnt(8)
	s_waitcnt lgkmcnt(0)
	s_barrier
	v_mfma_f32_16x16x32_bf16 v[138:141], v[126:129], v[220:223], v[138:141]
	v_mfma_f32_16x16x32_bf16 v[134:137], v[142:145], v[220:223], v[134:137]
	v_mfma_f32_16x16x32_bf16 v[122:125], v[126:129], v[228:231], v[122:125]
	v_mfma_f32_16x16x32_bf16 v[118:121], v[142:145], v[228:231], v[118:121]
	v_mfma_f32_16x16x32_bf16 v[106:109], v[126:129], v[236:239], v[106:109]
	v_mfma_f32_16x16x32_bf16 v[102:105], v[142:145], v[236:239], v[102:105]
	v_mfma_f32_16x16x32_bf16 v[90:93], v[126:129], v[244:247], v[90:93]
	v_mfma_f32_16x16x32_bf16 v[86:89], v[142:145], v[244:247], v[86:89]
	v_mfma_f32_16x16x32_bf16 v[138:141], v[130:133], v[224:227], v[138:141]
	v_mfma_f32_16x16x32_bf16 v[134:137], v[146:149], v[224:227], v[134:137]
	v_mfma_f32_16x16x32_bf16 v[122:125], v[130:133], v[232:235], v[122:125]
	v_mfma_f32_16x16x32_bf16 v[118:121], v[146:149], v[232:235], v[118:121]
	v_mfma_f32_16x16x32_bf16 v[106:109], v[130:133], v[240:243], v[106:109]
	v_mfma_f32_16x16x32_bf16 v[102:105], v[146:149], v[240:243], v[102:105]
	v_mfma_f32_16x16x32_bf16 v[90:93], v[130:133], v[248:251], v[90:93]
	v_mfma_f32_16x16x32_bf16 v[86:89], v[146:149], v[248:251], v[86:89]
	v_mfma_f32_16x16x32_bf16 v[114:117], v[166:169], v[220:223], v[114:117]
	v_mfma_f32_16x16x32_bf16 v[110:113], v[208:211], v[220:223], v[110:113]
	v_mfma_f32_16x16x32_bf16 v[98:101], v[166:169], v[228:231], v[98:101]
	v_mfma_f32_16x16x32_bf16 v[94:97], v[208:211], v[228:231], v[94:97]
	v_mfma_f32_16x16x32_bf16 v[82:85], v[166:169], v[236:239], v[82:85]
	v_mfma_f32_16x16x32_bf16 v[78:81], v[208:211], v[236:239], v[78:81]
	v_mfma_f32_16x16x32_bf16 v[66:69], v[166:169], v[244:247], v[66:69]
	v_mfma_f32_16x16x32_bf16 v[62:65], v[208:211], v[244:247], v[62:65]
	v_mfma_f32_16x16x32_bf16 v[114:117], v[204:207], v[224:227], v[114:117]
	v_mfma_f32_16x16x32_bf16 v[110:113], v[216:219], v[224:227], v[110:113]
	v_mfma_f32_16x16x32_bf16 v[98:101], v[204:207], v[232:235], v[98:101]
	v_mfma_f32_16x16x32_bf16 v[94:97], v[216:219], v[232:235], v[94:97]
	v_mfma_f32_16x16x32_bf16 v[82:85], v[204:207], v[240:243], v[82:85]
	v_mfma_f32_16x16x32_bf16 v[78:81], v[216:219], v[240:243], v[78:81]
	v_mfma_f32_16x16x32_bf16 v[66:69], v[204:207], v[248:251], v[66:69]
	v_mfma_f32_16x16x32_bf16 v[62:65], v[216:219], v[248:251], v[62:65]
	s_barrier
	s_add_i32 s52, s52, s33
	v_lshl_add_u64 v[170:171], s[24:25], 0, v[0:1]
	s_mov_b32 m0, s52
	ds_read_b128 v[220:223], v198 offset:16384
	ds_read_b128 v[224:227], v198 offset:17408
	ds_read_b128 v[228:231], v198 offset:18432
	ds_read_b128 v[232:235], v198 offset:19456
	ds_read_b128 v[236:239], v198 offset:20480
	ds_read_b128 v[240:243], v198 offset:21504
	ds_read_b128 v[244:247], v198 offset:22528
	ds_read_b128 v[248:251], v198 offset:23552
	global_load_lds_dwordx4 v[170:171], off
	s_add_i32 m0, s52, 0x2000
	s_add_u32 s52, s24, 0x80000
	v_lshl_add_u64 v[200:201], s[24:25], 0, v[154:155]
	s_addc_u32 s53, s25, 0
	s_add_i32 s54, s54, s33
	global_load_lds_dwordx4 v[200:201], off
	v_lshl_add_u64 v[6:7], s[52:53], 0, v[0:1]
	s_mov_b32 m0, s54
	v_lshl_add_u64 v[202:203], s[46:47], 0, v[150:151]
	global_load_lds_dwordx4 v[6:7], off
	v_lshl_add_u64 v[6:7], s[52:53], 0, v[154:155]
	s_add_i32 m0, s54, 0x2000
	v_lshl_add_u64 v[212:213], s[46:47], 0, v[152:153]
	global_load_lds_dwordx4 v[6:7], off
	s_mov_b32 m0, s79
	s_nop 0
	global_load_lds_dwordx4 v[202:203], off
	s_mov_b32 m0, s81
	s_nop 0
	global_load_lds_dwordx4 v[212:213], off
	s_waitcnt vmcnt(8)
	s_waitcnt lgkmcnt(0)
	s_barrier
	v_mfma_f32_16x16x32_bf16 v[74:77], v[126:129], v[220:223], v[74:77]
	v_mfma_f32_16x16x32_bf16 v[70:73], v[142:145], v[220:223], v[70:73]
	v_mfma_f32_16x16x32_bf16 v[58:61], v[126:129], v[228:231], v[58:61]
	v_mfma_f32_16x16x32_bf16 v[54:57], v[142:145], v[228:231], v[54:57]
	v_mfma_f32_16x16x32_bf16 v[42:45], v[126:129], v[236:239], v[42:45]
	v_mfma_f32_16x16x32_bf16 v[38:41], v[142:145], v[236:239], v[38:41]
	v_mfma_f32_16x16x32_bf16 v[22:25], v[126:129], v[244:247], v[22:25]
	v_mfma_f32_16x16x32_bf16 v[18:21], v[142:145], v[244:247], v[18:21]
	v_mfma_f32_16x16x32_bf16 v[74:77], v[130:133], v[224:227], v[74:77]
	v_mfma_f32_16x16x32_bf16 v[70:73], v[146:149], v[224:227], v[70:73]
	v_mfma_f32_16x16x32_bf16 v[58:61], v[130:133], v[232:235], v[58:61]
	v_mfma_f32_16x16x32_bf16 v[54:57], v[146:149], v[232:235], v[54:57]
	v_mfma_f32_16x16x32_bf16 v[42:45], v[130:133], v[240:243], v[42:45]
	v_mfma_f32_16x16x32_bf16 v[38:41], v[146:149], v[240:243], v[38:41]
	v_mfma_f32_16x16x32_bf16 v[22:25], v[130:133], v[248:251], v[22:25]
	v_mfma_f32_16x16x32_bf16 v[18:21], v[146:149], v[248:251], v[18:21]
	v_mfma_f32_16x16x32_bf16 v[50:53], v[166:169], v[220:223], v[50:53]
	v_mfma_f32_16x16x32_bf16 v[46:49], v[208:211], v[220:223], v[46:49]
	v_mfma_f32_16x16x32_bf16 v[34:37], v[166:169], v[228:231], v[34:37]
	v_mfma_f32_16x16x32_bf16 v[30:33], v[208:211], v[228:231], v[30:33]
	v_mfma_f32_16x16x32_bf16 v[26:29], v[166:169], v[236:239], v[26:29]
	v_mfma_f32_16x16x32_bf16 v[2:5], v[208:211], v[236:239], v[2:5]
	v_mfma_f32_16x16x32_bf16 v[12:15], v[166:169], v[244:247], v[12:15]
	v_mfma_f32_16x16x32_bf16 v[6:9], v[208:211], v[244:247], v[8:11]
	v_mfma_f32_16x16x32_bf16 v[50:53], v[204:207], v[224:227], v[50:53]
	v_mfma_f32_16x16x32_bf16 v[46:49], v[216:219], v[224:227], v[46:49]
	v_mfma_f32_16x16x32_bf16 v[34:37], v[204:207], v[232:235], v[34:37]
	v_mfma_f32_16x16x32_bf16 v[30:33], v[216:219], v[232:235], v[30:33]
	v_mfma_f32_16x16x32_bf16 v[26:29], v[204:207], v[240:243], v[26:29]
	v_mfma_f32_16x16x32_bf16 v[2:5], v[216:219], v[240:243], v[2:5]
	v_mfma_f32_16x16x32_bf16 v[12:15], v[204:207], v[248:251], v[12:15]
	v_mfma_f32_16x16x32_bf16 v[6:9], v[216:219], v[248:251], v[6:9]
	s_barrier
	s_add_i32 s52, 0, 0x18000
	v_add_u32_e32 v10, s52, v172
	s_add_i32 s53, 0, 0x1c000
	ds_read_b128 v[126:129], v10
	ds_read_b128 v[130:133], v10 offset:1024
	ds_read_b128 v[142:145], v10 offset:2048
	ds_read_b128 v[146:149], v10 offset:3072
	v_add_u32_e32 v10, s53, v172
	ds_read_b128 v[166:169], v10
	ds_read_b128 v[204:207], v10 offset:1024
	ds_read_b128 v[208:211], v10 offset:2048
	ds_read_b128 v[216:219], v10 offset:3072
	s_add_u32 s46, s46, 0x80000
	s_addc_u32 s47, s47, 0
	s_mov_b32 m0, s82
	v_lshl_add_u64 v[10:11], s[46:47], 0, v[150:151]
	ds_read_b128 v[220:223], v198 offset:32768
	ds_read_b128 v[224:227], v198 offset:33792
	ds_read_b128 v[228:231], v198 offset:34816
	ds_read_b128 v[232:235], v198 offset:35840
	ds_read_b128 v[236:239], v198 offset:36864
	ds_read_b128 v[240:243], v198 offset:37888
	ds_read_b128 v[244:247], v198 offset:38912
	ds_read_b128 v[248:251], v198 offset:39936
	global_load_lds_dwordx4 v[10:11], off
	v_lshl_add_u64 v[10:11], s[46:47], 0, v[152:153]
	s_mov_b32 m0, s83
	s_nop 0
	global_load_lds_dwordx4 v[10:11], off
	s_waitcnt vmcnt(8)
	s_waitcnt lgkmcnt(0)
	s_barrier
	v_mfma_f32_16x16x32_bf16 v[138:141], v[126:129], v[220:223], v[138:141]
	v_mfma_f32_16x16x32_bf16 v[134:137], v[142:145], v[220:223], v[134:137]
	v_mfma_f32_16x16x32_bf16 v[122:125], v[126:129], v[228:231], v[122:125]
	v_mfma_f32_16x16x32_bf16 v[118:121], v[142:145], v[228:231], v[118:121]
	v_mfma_f32_16x16x32_bf16 v[106:109], v[126:129], v[236:239], v[106:109]
	v_mfma_f32_16x16x32_bf16 v[102:105], v[142:145], v[236:239], v[102:105]
	v_mfma_f32_16x16x32_bf16 v[90:93], v[126:129], v[244:247], v[90:93]
	v_mfma_f32_16x16x32_bf16 v[86:89], v[142:145], v[244:247], v[86:89]
	v_mfma_f32_16x16x32_bf16 v[138:141], v[130:133], v[224:227], v[138:141]
	v_mfma_f32_16x16x32_bf16 v[134:137], v[146:149], v[224:227], v[134:137]
	v_mfma_f32_16x16x32_bf16 v[122:125], v[130:133], v[232:235], v[122:125]
	v_mfma_f32_16x16x32_bf16 v[118:121], v[146:149], v[232:235], v[118:121]
	v_mfma_f32_16x16x32_bf16 v[106:109], v[130:133], v[240:243], v[106:109]
	v_mfma_f32_16x16x32_bf16 v[102:105], v[146:149], v[240:243], v[102:105]
	v_mfma_f32_16x16x32_bf16 v[90:93], v[130:133], v[248:251], v[90:93]
	v_mfma_f32_16x16x32_bf16 v[86:89], v[146:149], v[248:251], v[86:89]
	v_mfma_f32_16x16x32_bf16 v[114:117], v[166:169], v[220:223], v[114:117]
	v_mfma_f32_16x16x32_bf16 v[110:113], v[208:211], v[220:223], v[110:113]
	v_mfma_f32_16x16x32_bf16 v[98:101], v[166:169], v[228:231], v[98:101]
	v_mfma_f32_16x16x32_bf16 v[94:97], v[208:211], v[228:231], v[94:97]
	v_mfma_f32_16x16x32_bf16 v[82:85], v[166:169], v[236:239], v[82:85]
	v_mfma_f32_16x16x32_bf16 v[78:81], v[208:211], v[236:239], v[78:81]
	v_mfma_f32_16x16x32_bf16 v[66:69], v[166:169], v[244:247], v[66:69]
	v_mfma_f32_16x16x32_bf16 v[62:65], v[208:211], v[244:247], v[62:65]
	v_mfma_f32_16x16x32_bf16 v[114:117], v[204:207], v[224:227], v[114:117]
	v_mfma_f32_16x16x32_bf16 v[110:113], v[216:219], v[224:227], v[110:113]
	v_mfma_f32_16x16x32_bf16 v[98:101], v[204:207], v[232:235], v[98:101]
	v_mfma_f32_16x16x32_bf16 v[94:97], v[216:219], v[232:235], v[94:97]
	v_mfma_f32_16x16x32_bf16 v[82:85], v[204:207], v[240:243], v[82:85]
	v_mfma_f32_16x16x32_bf16 v[78:81], v[216:219], v[240:243], v[78:81]
	v_mfma_f32_16x16x32_bf16 v[66:69], v[204:207], v[248:251], v[66:69]
	v_mfma_f32_16x16x32_bf16 v[62:65], v[216:219], v[248:251], v[62:65]
	s_barrier
	s_add_i32 s46, s52, s33
	v_lshl_add_u64 v[10:11], v[170:171], 0, s[36:37]
	s_mov_b32 m0, s46
	ds_read_b128 v[220:223], v198 offset:49152
	ds_read_b128 v[224:227], v198 offset:50176
	ds_read_b128 v[228:231], v198 offset:51200
	ds_read_b128 v[232:235], v198 offset:52224
	ds_read_b128 v[236:239], v198 offset:53248
	ds_read_b128 v[240:243], v198 offset:54272
	ds_read_b128 v[244:247], v198 offset:55296
	ds_read_b128 v[248:251], v198 offset:56320
	global_load_lds_dwordx4 v[10:11], off
	s_add_i32 m0, s46, 0x2000
	s_add_u32 s24, s24, 0x80080
	v_lshl_add_u64 v[10:11], v[200:201], 0, s[36:37]
	s_addc_u32 s25, s25, 0
	s_add_i32 s46, s53, s33
	global_load_lds_dwordx4 v[10:11], off
	v_lshl_add_u64 v[10:11], s[24:25], 0, v[0:1]
	s_mov_b32 m0, s46
	s_nop 0
	global_load_lds_dwordx4 v[10:11], off
	v_lshl_add_u64 v[10:11], s[24:25], 0, v[154:155]
	s_add_i32 m0, s46, 0x2000
	s_nop 0
	global_load_lds_dwordx4 v[10:11], off
	v_lshl_add_u64 v[10:11], v[202:203], 0, s[36:37]
	s_mov_b32 m0, s94
	s_nop 0
	global_load_lds_dwordx4 v[10:11], off
	v_lshl_add_u64 v[10:11], v[212:213], 0, s[36:37]
	s_mov_b32 m0, s95
	s_nop 0
	global_load_lds_dwordx4 v[10:11], off
	s_add_i32 s51, s51, 2
	s_add_u32 s18, s18, 0x100
	s_addc_u32 s19, s19, 0
	s_add_u32 s29, s29, 0x100
	s_addc_u32 s50, s50, 0
	s_cmp_gt_u32 s51, 29
	s_waitcnt vmcnt(8)
	s_waitcnt lgkmcnt(0)
	s_barrier
	v_mfma_f32_16x16x32_bf16 v[74:77], v[126:129], v[220:223], v[74:77]
	v_mfma_f32_16x16x32_bf16 v[70:73], v[142:145], v[220:223], v[70:73]
	v_mfma_f32_16x16x32_bf16 v[58:61], v[126:129], v[228:231], v[58:61]
	v_mfma_f32_16x16x32_bf16 v[54:57], v[142:145], v[228:231], v[54:57]
	v_mfma_f32_16x16x32_bf16 v[42:45], v[126:129], v[236:239], v[42:45]
	v_mfma_f32_16x16x32_bf16 v[38:41], v[142:145], v[236:239], v[38:41]
	v_mfma_f32_16x16x32_bf16 v[22:25], v[126:129], v[244:247], v[22:25]
	v_mfma_f32_16x16x32_bf16 v[18:21], v[142:145], v[244:247], v[18:21]
	v_mfma_f32_16x16x32_bf16 v[74:77], v[130:133], v[224:227], v[74:77]
	v_mfma_f32_16x16x32_bf16 v[70:73], v[146:149], v[224:227], v[70:73]
	v_mfma_f32_16x16x32_bf16 v[58:61], v[130:133], v[232:235], v[58:61]
	v_mfma_f32_16x16x32_bf16 v[54:57], v[146:149], v[232:235], v[54:57]
	v_mfma_f32_16x16x32_bf16 v[42:45], v[130:133], v[240:243], v[42:45]
	v_mfma_f32_16x16x32_bf16 v[38:41], v[146:149], v[240:243], v[38:41]
	v_mfma_f32_16x16x32_bf16 v[22:25], v[130:133], v[248:251], v[22:25]
	v_mfma_f32_16x16x32_bf16 v[18:21], v[146:149], v[248:251], v[18:21]
	v_mfma_f32_16x16x32_bf16 v[50:53], v[166:169], v[220:223], v[50:53]
	v_mfma_f32_16x16x32_bf16 v[46:49], v[208:211], v[220:223], v[46:49]
	v_mfma_f32_16x16x32_bf16 v[34:37], v[166:169], v[228:231], v[34:37]
	v_mfma_f32_16x16x32_bf16 v[30:33], v[208:211], v[228:231], v[30:33]
	v_mfma_f32_16x16x32_bf16 v[26:29], v[166:169], v[236:239], v[26:29]
	v_mfma_f32_16x16x32_bf16 v[2:5], v[208:211], v[236:239], v[2:5]
	v_mfma_f32_16x16x32_bf16 v[10:13], v[166:169], v[244:247], v[12:15]
	v_mfma_f32_16x16x32_bf16 v[6:9], v[208:211], v[244:247], v[6:9]
	v_mfma_f32_16x16x32_bf16 v[50:53], v[204:207], v[224:227], v[50:53]
	v_mfma_f32_16x16x32_bf16 v[46:49], v[216:219], v[224:227], v[46:49]
	v_mfma_f32_16x16x32_bf16 v[34:37], v[204:207], v[232:235], v[34:37]
	v_mfma_f32_16x16x32_bf16 v[30:33], v[216:219], v[232:235], v[30:33]
	v_mfma_f32_16x16x32_bf16 v[26:29], v[204:207], v[240:243], v[26:29]
	v_mfma_f32_16x16x32_bf16 v[2:5], v[216:219], v[240:243], v[2:5]
	v_mfma_f32_16x16x32_bf16 v[12:15], v[204:207], v[248:251], v[10:13]
	v_mfma_f32_16x16x32_bf16 v[8:11], v[216:219], v[248:251], v[6:9]
	s_barrier
	s_cbranch_scc0 .LBB0_164
	s_and_b64 vcc, exec, s[10:11]
	s_cbranch_vccz .LBB0_167
	s_barrier

.LBB0_756:
	s_add_u32 s44, s42, 0xfff80080
	s_addc_u32 s45, s43, -1
	s_add_i32 s62, 0, 0x10000
	s_cmp_eq_u32 s61, 28
	s_cselect_b32 s47, s1, s45
	s_cselect_b32 s46, s21, s44
	v_add_u32_e32 v146, s62, v148
	s_cselect_b32 s45, s19, s51
	s_cselect_b32 s44, s27, s29
	s_add_i32 s64, 0, 0x14000
	ds_read_b128 v[138:141], v146
	ds_read_b128 v[142:145], v146 offset:1024
	ds_read_b128 v[154:157], v146 offset:2048
	ds_read_b128 v[158:161], v146 offset:3072
	v_add_u32_e32 v146, s64, v148
	ds_read_b128 v[162:165], v146
	ds_read_b128 v[166:169], v146 offset:1024
	ds_read_b128 v[170:173], v146 offset:2048
	ds_read_b128 v[174:177], v146 offset:3072
	v_lshl_add_u64 v[146:147], s[42:43], 0, v[134:135]
	s_add_i32 m0, s50, 0xc000
	ds_read_b128 v[178:181], v152
	ds_read_b128 v[182:185], v152 offset:1024
	ds_read_b128 v[186:189], v152 offset:2048
	ds_read_b128 v[190:193], v152 offset:3072
	ds_read_b128 v[194:197], v152 offset:4096
	ds_read_b128 v[198:201], v152 offset:5120
	ds_read_b128 v[202:205], v152 offset:6144
	ds_read_b128 v[206:209], v152 offset:7168
	global_load_lds_dwordx4 v[146:147], off
	v_lshl_add_u64 v[146:147], s[42:43], 0, v[136:137]
	s_add_i32 m0, s50, 0xe000
	s_nop 0
	global_load_lds_dwordx4 v[146:147], off
	s_waitcnt vmcnt(8)
	s_waitcnt lgkmcnt(0)
	s_barrier
	v_mfma_f32_16x16x32_bf16 v[130:133], v[138:141], v[178:181], v[130:133]
	v_mfma_f32_16x16x32_bf16 v[126:129], v[154:157], v[178:181], v[126:129]
	v_mfma_f32_16x16x32_bf16 v[114:117], v[138:141], v[186:189], v[114:117]
	v_mfma_f32_16x16x32_bf16 v[110:113], v[154:157], v[186:189], v[110:113]
	v_mfma_f32_16x16x32_bf16 v[98:101], v[138:141], v[194:197], v[98:101]
	v_mfma_f32_16x16x32_bf16 v[94:97], v[154:157], v[194:197], v[94:97]
	v_mfma_f32_16x16x32_bf16 v[82:85], v[138:141], v[202:205], v[82:85]
	v_mfma_f32_16x16x32_bf16 v[78:81], v[154:157], v[202:205], v[78:81]
	v_mfma_f32_16x16x32_bf16 v[130:133], v[142:145], v[182:185], v[130:133]
	v_mfma_f32_16x16x32_bf16 v[126:129], v[158:161], v[182:185], v[126:129]
	v_mfma_f32_16x16x32_bf16 v[114:117], v[142:145], v[190:193], v[114:117]
	v_mfma_f32_16x16x32_bf16 v[110:113], v[158:161], v[190:193], v[110:113]
	v_mfma_f32_16x16x32_bf16 v[98:101], v[142:145], v[198:201], v[98:101]
	v_mfma_f32_16x16x32_bf16 v[94:97], v[158:161], v[198:201], v[94:97]
	v_mfma_f32_16x16x32_bf16 v[82:85], v[142:145], v[206:209], v[82:85]
	v_mfma_f32_16x16x32_bf16 v[78:81], v[158:161], v[206:209], v[78:81]
	v_mfma_f32_16x16x32_bf16 v[122:125], v[162:165], v[178:181], v[122:125]
	v_mfma_f32_16x16x32_bf16 v[118:121], v[170:173], v[178:181], v[118:121]
	v_mfma_f32_16x16x32_bf16 v[106:109], v[162:165], v[186:189], v[106:109]
	v_mfma_f32_16x16x32_bf16 v[102:105], v[170:173], v[186:189], v[102:105]
	v_mfma_f32_16x16x32_bf16 v[90:93], v[162:165], v[194:197], v[90:93]
	v_mfma_f32_16x16x32_bf16 v[86:89], v[170:173], v[194:197], v[86:89]
	v_mfma_f32_16x16x32_bf16 v[74:77], v[162:165], v[202:205], v[74:77]
	v_mfma_f32_16x16x32_bf16 v[70:73], v[170:173], v[202:205], v[70:73]
	v_mfma_f32_16x16x32_bf16 v[122:125], v[166:169], v[182:185], v[122:125]
	v_mfma_f32_16x16x32_bf16 v[118:121], v[174:177], v[182:185], v[118:121]
	v_mfma_f32_16x16x32_bf16 v[106:109], v[166:169], v[190:193], v[106:109]
	v_mfma_f32_16x16x32_bf16 v[102:105], v[174:177], v[190:193], v[102:105]
	v_mfma_f32_16x16x32_bf16 v[90:93], v[166:169], v[198:201], v[90:93]
	v_mfma_f32_16x16x32_bf16 v[86:89], v[174:177], v[198:201], v[86:89]
	v_mfma_f32_16x16x32_bf16 v[74:77], v[166:169], v[206:209], v[74:77]
	v_mfma_f32_16x16x32_bf16 v[70:73], v[174:177], v[206:209], v[70:73]
	s_barrier
	s_add_i32 s62, s62, s33
	v_lshl_add_u64 v[146:147], s[44:45], 0, v[0:1]
	s_mov_b32 m0, s62
	ds_read_b128 v[178:181], v152 offset:16384
	ds_read_b128 v[182:185], v152 offset:17408
	ds_read_b128 v[186:189], v152 offset:18432
	ds_read_b128 v[190:193], v152 offset:19456
	ds_read_b128 v[194:197], v152 offset:20480
	ds_read_b128 v[198:201], v152 offset:21504
	ds_read_b128 v[202:205], v152 offset:22528
	ds_read_b128 v[206:209], v152 offset:23552
	global_load_lds_dwordx4 v[146:147], off
	s_add_i32 m0, s62, 0x2000
	s_add_u32 s62, s44, 0x80000
	v_lshl_add_u64 v[210:211], s[44:45], 0, v[14:15]
	s_addc_u32 s63, s45, 0
	s_add_i32 s64, s64, s33
	global_load_lds_dwordx4 v[210:211], off
	v_lshl_add_u64 v[212:213], s[62:63], 0, v[0:1]
	s_mov_b32 m0, s64
	v_lshl_add_u64 v[214:215], s[46:47], 0, v[14:15]
	global_load_lds_dwordx4 v[212:213], off
	v_lshl_add_u64 v[212:213], s[62:63], 0, v[14:15]
	s_add_i32 m0, s64, 0x2000
	s_nop 0
	global_load_lds_dwordx4 v[212:213], off
	v_lshl_add_u64 v[212:213], s[46:47], 0, v[0:1]
	s_mov_b32 m0, s50
	s_nop 0
	global_load_lds_dwordx4 v[212:213], off
	s_mov_b32 m0, s52
	s_nop 0
	global_load_lds_dwordx4 v[214:215], off
	s_waitcnt vmcnt(8)
	s_waitcnt lgkmcnt(0)
	s_barrier
	v_mfma_f32_16x16x32_bf16 v[66:69], v[138:141], v[178:181], v[66:69]
	v_mfma_f32_16x16x32_bf16 v[62:65], v[154:157], v[178:181], v[62:65]
	v_mfma_f32_16x16x32_bf16 v[50:53], v[138:141], v[186:189], v[50:53]
	v_mfma_f32_16x16x32_bf16 v[46:49], v[154:157], v[186:189], v[46:49]
	v_mfma_f32_16x16x32_bf16 v[34:37], v[138:141], v[194:197], v[34:37]
	v_mfma_f32_16x16x32_bf16 v[30:33], v[154:157], v[194:197], v[30:33]
	v_mfma_f32_16x16x32_bf16 v[18:21], v[138:141], v[202:205], v[18:21]
	v_mfma_f32_16x16x32_bf16 v[10:13], v[154:157], v[202:205], v[10:13]
	v_mfma_f32_16x16x32_bf16 v[66:69], v[142:145], v[182:185], v[66:69]
	v_mfma_f32_16x16x32_bf16 v[62:65], v[158:161], v[182:185], v[62:65]
	v_mfma_f32_16x16x32_bf16 v[50:53], v[142:145], v[190:193], v[50:53]
	v_mfma_f32_16x16x32_bf16 v[46:49], v[158:161], v[190:193], v[46:49]
	v_mfma_f32_16x16x32_bf16 v[34:37], v[142:145], v[198:201], v[34:37]
	v_mfma_f32_16x16x32_bf16 v[30:33], v[158:161], v[198:201], v[30:33]
	v_mfma_f32_16x16x32_bf16 v[18:21], v[142:145], v[206:209], v[18:21]
	v_mfma_f32_16x16x32_bf16 v[10:13], v[158:161], v[206:209], v[10:13]
	v_mfma_f32_16x16x32_bf16 v[58:61], v[162:165], v[178:181], v[58:61]
	v_mfma_f32_16x16x32_bf16 v[54:57], v[170:173], v[178:181], v[54:57]
	v_mfma_f32_16x16x32_bf16 v[42:45], v[162:165], v[186:189], v[42:45]
	v_mfma_f32_16x16x32_bf16 v[38:41], v[170:173], v[186:189], v[38:41]
	v_mfma_f32_16x16x32_bf16 v[26:29], v[162:165], v[194:197], v[26:29]
	v_mfma_f32_16x16x32_bf16 v[22:25], v[170:173], v[194:197], v[22:25]
	v_mfma_f32_16x16x32_bf16 v[6:9], v[162:165], v[202:205], v[6:9]
	v_mfma_f32_16x16x32_bf16 v[2:5], v[170:173], v[202:205], v[2:5]
	v_mfma_f32_16x16x32_bf16 v[58:61], v[166:169], v[182:185], v[58:61]
	v_mfma_f32_16x16x32_bf16 v[54:57], v[174:177], v[182:185], v[54:57]
	v_mfma_f32_16x16x32_bf16 v[42:45], v[166:169], v[190:193], v[42:45]
	v_mfma_f32_16x16x32_bf16 v[38:41], v[174:177], v[190:193], v[38:41]
	v_mfma_f32_16x16x32_bf16 v[26:29], v[166:169], v[198:201], v[26:29]
	v_mfma_f32_16x16x32_bf16 v[22:25], v[174:177], v[198:201], v[22:25]
	v_mfma_f32_16x16x32_bf16 v[6:9], v[166:169], v[206:209], v[6:9]
	v_mfma_f32_16x16x32_bf16 v[2:5], v[174:177], v[206:209], v[2:5]
	s_barrier
	s_add_i32 s62, 0, 0x18000
	s_add_i32 s63, 0, 0x1c000
	v_add_u32_e32 v158, s62, v148
	v_add_u32_e32 v174, s63, v148
	ds_read_b128 v[138:141], v158
	ds_read_b128 v[142:145], v158 offset:1024
	ds_read_b128 v[154:157], v158 offset:2048
	ds_read_b128 v[158:161], v158 offset:3072
	ds_read_b128 v[162:165], v174
	ds_read_b128 v[166:169], v174 offset:1024
	ds_read_b128 v[170:173], v174 offset:2048
	ds_read_b128 v[174:177], v174 offset:3072
	s_add_u32 s46, s46, 0x80000
	s_addc_u32 s47, s47, 0
	s_mov_b32 m0, s53
	v_lshl_add_u64 v[216:217], s[46:47], 0, v[0:1]
	ds_read_b128 v[178:181], v152 offset:32768
	ds_read_b128 v[182:185], v152 offset:33792
	ds_read_b128 v[186:189], v152 offset:34816
	ds_read_b128 v[190:193], v152 offset:35840
	ds_read_b128 v[194:197], v152 offset:36864
	ds_read_b128 v[198:201], v152 offset:37888
	ds_read_b128 v[202:205], v152 offset:38912
	ds_read_b128 v[206:209], v152 offset:39936
	global_load_lds_dwordx4 v[216:217], off
	v_lshl_add_u64 v[216:217], s[46:47], 0, v[14:15]
	s_mov_b32 m0, s54
	s_nop 0
	global_load_lds_dwordx4 v[216:217], off
	s_waitcnt vmcnt(8)
	s_waitcnt lgkmcnt(0)
	s_barrier
	v_mfma_f32_16x16x32_bf16 v[130:133], v[138:141], v[178:181], v[130:133]
	v_mfma_f32_16x16x32_bf16 v[126:129], v[154:157], v[178:181], v[126:129]
	v_mfma_f32_16x16x32_bf16 v[114:117], v[138:141], v[186:189], v[114:117]
	v_mfma_f32_16x16x32_bf16 v[110:113], v[154:157], v[186:189], v[110:113]
	v_mfma_f32_16x16x32_bf16 v[98:101], v[138:141], v[194:197], v[98:101]
	v_mfma_f32_16x16x32_bf16 v[94:97], v[154:157], v[194:197], v[94:97]
	v_mfma_f32_16x16x32_bf16 v[82:85], v[138:141], v[202:205], v[82:85]
	v_mfma_f32_16x16x32_bf16 v[78:81], v[154:157], v[202:205], v[78:81]
	v_mfma_f32_16x16x32_bf16 v[130:133], v[142:145], v[182:185], v[130:133]
	v_mfma_f32_16x16x32_bf16 v[126:129], v[158:161], v[182:185], v[126:129]
	v_mfma_f32_16x16x32_bf16 v[114:117], v[142:145], v[190:193], v[114:117]
	v_mfma_f32_16x16x32_bf16 v[110:113], v[158:161], v[190:193], v[110:113]
	v_mfma_f32_16x16x32_bf16 v[98:101], v[142:145], v[198:201], v[98:101]
	v_mfma_f32_16x16x32_bf16 v[94:97], v[158:161], v[198:201], v[94:97]
	v_mfma_f32_16x16x32_bf16 v[82:85], v[142:145], v[206:209], v[82:85]
	v_mfma_f32_16x16x32_bf16 v[78:81], v[158:161], v[206:209], v[78:81]
	v_mfma_f32_16x16x32_bf16 v[122:125], v[162:165], v[178:181], v[122:125]
	v_mfma_f32_16x16x32_bf16 v[118:121], v[170:173], v[178:181], v[118:121]
	v_mfma_f32_16x16x32_bf16 v[106:109], v[162:165], v[186:189], v[106:109]
	v_mfma_f32_16x16x32_bf16 v[102:105], v[170:173], v[186:189], v[102:105]
	v_mfma_f32_16x16x32_bf16 v[90:93], v[162:165], v[194:197], v[90:93]
	v_mfma_f32_16x16x32_bf16 v[86:89], v[170:173], v[194:197], v[86:89]
	v_mfma_f32_16x16x32_bf16 v[74:77], v[162:165], v[202:205], v[74:77]
	v_mfma_f32_16x16x32_bf16 v[70:73], v[170:173], v[202:205], v[70:73]
	v_mfma_f32_16x16x32_bf16 v[122:125], v[166:169], v[182:185], v[122:125]
	v_mfma_f32_16x16x32_bf16 v[118:121], v[174:177], v[182:185], v[118:121]
	v_mfma_f32_16x16x32_bf16 v[106:109], v[166:169], v[190:193], v[106:109]
	v_mfma_f32_16x16x32_bf16 v[102:105], v[174:177], v[190:193], v[102:105]
	v_mfma_f32_16x16x32_bf16 v[90:93], v[166:169], v[198:201], v[90:93]
	v_mfma_f32_16x16x32_bf16 v[86:89], v[174:177], v[198:201], v[86:89]
	v_mfma_f32_16x16x32_bf16 v[74:77], v[166:169], v[206:209], v[74:77]
	v_mfma_f32_16x16x32_bf16 v[70:73], v[174:177], v[206:209], v[70:73]
	s_barrier
	s_add_i32 s46, s62, s33
	v_lshl_add_u64 v[146:147], v[146:147], 0, s[36:37]
	s_mov_b32 m0, s46
	ds_read_b128 v[178:181], v152 offset:49152
	ds_read_b128 v[182:185], v152 offset:50176
	ds_read_b128 v[186:189], v152 offset:51200
	ds_read_b128 v[190:193], v152 offset:52224
	ds_read_b128 v[194:197], v152 offset:53248
	ds_read_b128 v[198:201], v152 offset:54272
	ds_read_b128 v[202:205], v152 offset:55296
	ds_read_b128 v[206:209], v152 offset:56320
	global_load_lds_dwordx4 v[146:147], off
	s_add_i32 m0, s46, 0x2000
	s_add_u32 s44, s44, 0x80080
	v_lshl_add_u64 v[146:147], v[210:211], 0, s[36:37]
	s_addc_u32 s45, s45, 0
	s_add_i32 s46, s63, s33
	global_load_lds_dwordx4 v[146:147], off
	v_lshl_add_u64 v[146:147], s[44:45], 0, v[0:1]
	s_mov_b32 m0, s46
	s_nop 0
	global_load_lds_dwordx4 v[146:147], off
	v_lshl_add_u64 v[146:147], s[44:45], 0, v[14:15]
	s_add_i32 m0, s46, 0x2000
	s_nop 0
	global_load_lds_dwordx4 v[146:147], off
	v_lshl_add_u64 v[146:147], v[212:213], 0, s[36:37]
	s_mov_b32 m0, s56
	s_nop 0
	global_load_lds_dwordx4 v[146:147], off
	v_lshl_add_u64 v[146:147], v[214:215], 0, s[36:37]
	s_mov_b32 m0, s57
	s_nop 0
	global_load_lds_dwordx4 v[146:147], off
	s_add_i32 s61, s61, 2
	s_add_u32 s42, s42, 0x100
	s_addc_u32 s43, s43, 0
	s_add_u32 s29, s29, 0x100
	s_addc_u32 s51, s51, 0
	s_cmp_gt_u32 s61, 29
	s_waitcnt vmcnt(8)
	s_waitcnt lgkmcnt(0)
	s_barrier
	v_mfma_f32_16x16x32_bf16 v[66:69], v[138:141], v[178:181], v[66:69]
	v_mfma_f32_16x16x32_bf16 v[62:65], v[154:157], v[178:181], v[62:65]
	v_mfma_f32_16x16x32_bf16 v[50:53], v[138:141], v[186:189], v[50:53]
	v_mfma_f32_16x16x32_bf16 v[46:49], v[154:157], v[186:189], v[46:49]
	v_mfma_f32_16x16x32_bf16 v[34:37], v[138:141], v[194:197], v[34:37]
	v_mfma_f32_16x16x32_bf16 v[30:33], v[154:157], v[194:197], v[30:33]
	v_mfma_f32_16x16x32_bf16 v[18:21], v[138:141], v[202:205], v[18:21]
	v_mfma_f32_16x16x32_bf16 v[10:13], v[154:157], v[202:205], v[10:13]
	v_mfma_f32_16x16x32_bf16 v[66:69], v[142:145], v[182:185], v[66:69]
	v_mfma_f32_16x16x32_bf16 v[62:65], v[158:161], v[182:185], v[62:65]
	v_mfma_f32_16x16x32_bf16 v[50:53], v[142:145], v[190:193], v[50:53]
	v_mfma_f32_16x16x32_bf16 v[46:49], v[158:161], v[190:193], v[46:49]
	v_mfma_f32_16x16x32_bf16 v[34:37], v[142:145], v[198:201], v[34:37]
	v_mfma_f32_16x16x32_bf16 v[30:33], v[158:161], v[198:201], v[30:33]
	v_mfma_f32_16x16x32_bf16 v[18:21], v[142:145], v[206:209], v[18:21]
	v_mfma_f32_16x16x32_bf16 v[10:13], v[158:161], v[206:209], v[10:13]
	v_mfma_f32_16x16x32_bf16 v[58:61], v[162:165], v[178:181], v[58:61]
	v_mfma_f32_16x16x32_bf16 v[54:57], v[170:173], v[178:181], v[54:57]
	v_mfma_f32_16x16x32_bf16 v[42:45], v[162:165], v[186:189], v[42:45]
	v_mfma_f32_16x16x32_bf16 v[38:41], v[170:173], v[186:189], v[38:41]
	v_mfma_f32_16x16x32_bf16 v[26:29], v[162:165], v[194:197], v[26:29]
	v_mfma_f32_16x16x32_bf16 v[22:25], v[170:173], v[194:197], v[22:25]
	v_mfma_f32_16x16x32_bf16 v[6:9], v[162:165], v[202:205], v[6:9]
	v_mfma_f32_16x16x32_bf16 v[2:5], v[170:173], v[202:205], v[2:5]
	v_mfma_f32_16x16x32_bf16 v[58:61], v[166:169], v[182:185], v[58:61]
	v_mfma_f32_16x16x32_bf16 v[54:57], v[174:177], v[182:185], v[54:57]
	v_mfma_f32_16x16x32_bf16 v[42:45], v[166:169], v[190:193], v[42:45]
	v_mfma_f32_16x16x32_bf16 v[38:41], v[174:177], v[190:193], v[38:41]
	v_mfma_f32_16x16x32_bf16 v[26:29], v[166:169], v[198:201], v[26:29]
	v_mfma_f32_16x16x32_bf16 v[22:25], v[174:177], v[198:201], v[22:25]
	v_mfma_f32_16x16x32_bf16 v[6:9], v[166:169], v[206:209], v[6:9]
	v_mfma_f32_16x16x32_bf16 v[2:5], v[174:177], v[206:209], v[2:5]
	s_barrier
	s_cbranch_scc0 .LBB0_756
	s_and_b64 vcc, exec, s[10:11]
	s_cbranch_vccz .LBB0_759
	s_barrier

.LBB0_878:
	s_add_u32 s20, s8, 0xfff80080
	s_addc_u32 s21, s9, -1
	s_add_i32 s53, 0, 0x10000
	s_cmp_eq_u32 s52, 28
	s_cselect_b32 s23, s7, s21
	s_cselect_b32 s22, s25, s20
	v_add_u32_e32 v6, s53, v170
	s_cselect_b32 s21, s5, s51
	s_cselect_b32 s20, s47, s50
	s_add_i32 s54, 0, 0x14000
	ds_read_b128 v[126:129], v6
	ds_read_b128 v[130:133], v6 offset:1024
	ds_read_b128 v[142:145], v6 offset:2048
	ds_read_b128 v[146:149], v6 offset:3072
	v_add_u32_e32 v6, s54, v170
	ds_read_b128 v[164:167], v6
	ds_read_b128 v[204:207], v6 offset:1024
	ds_read_b128 v[208:211], v6 offset:2048
	ds_read_b128 v[216:219], v6 offset:3072
	v_lshl_add_u64 v[6:7], s[8:9], 0, v[160:161]
	s_add_i32 m0, s38, 0xc000
	ds_read_b128 v[220:223], v196
	ds_read_b128 v[224:227], v196 offset:1024
	ds_read_b128 v[228:231], v196 offset:2048
	ds_read_b128 v[232:235], v196 offset:3072
	ds_read_b128 v[236:239], v196 offset:4096
	ds_read_b128 v[240:243], v196 offset:5120
	ds_read_b128 v[244:247], v196 offset:6144
	ds_read_b128 v[248:251], v196 offset:7168
	global_load_lds_dwordx4 v[6:7], off
	v_lshl_add_u64 v[6:7], s[8:9], 0, v[162:163]
	s_add_i32 m0, s38, 0xe000
	s_nop 0
	global_load_lds_dwordx4 v[6:7], off
	s_waitcnt vmcnt(8)
	s_waitcnt lgkmcnt(0)
	s_barrier
	v_mfma_f32_16x16x32_bf16 v[138:141], v[126:129], v[220:223], v[138:141]
	v_mfma_f32_16x16x32_bf16 v[134:137], v[142:145], v[220:223], v[134:137]
	v_mfma_f32_16x16x32_bf16 v[122:125], v[126:129], v[228:231], v[122:125]
	v_mfma_f32_16x16x32_bf16 v[118:121], v[142:145], v[228:231], v[118:121]
	v_mfma_f32_16x16x32_bf16 v[106:109], v[126:129], v[236:239], v[106:109]
	v_mfma_f32_16x16x32_bf16 v[102:105], v[142:145], v[236:239], v[102:105]
	v_mfma_f32_16x16x32_bf16 v[90:93], v[126:129], v[244:247], v[90:93]
	v_mfma_f32_16x16x32_bf16 v[86:89], v[142:145], v[244:247], v[86:89]
	v_mfma_f32_16x16x32_bf16 v[138:141], v[130:133], v[224:227], v[138:141]
	v_mfma_f32_16x16x32_bf16 v[134:137], v[146:149], v[224:227], v[134:137]
	v_mfma_f32_16x16x32_bf16 v[122:125], v[130:133], v[232:235], v[122:125]
	v_mfma_f32_16x16x32_bf16 v[118:121], v[146:149], v[232:235], v[118:121]
	v_mfma_f32_16x16x32_bf16 v[106:109], v[130:133], v[240:243], v[106:109]
	v_mfma_f32_16x16x32_bf16 v[102:105], v[146:149], v[240:243], v[102:105]
	v_mfma_f32_16x16x32_bf16 v[90:93], v[130:133], v[248:251], v[90:93]
	v_mfma_f32_16x16x32_bf16 v[86:89], v[146:149], v[248:251], v[86:89]
	v_mfma_f32_16x16x32_bf16 v[114:117], v[164:167], v[220:223], v[114:117]
	v_mfma_f32_16x16x32_bf16 v[110:113], v[208:211], v[220:223], v[110:113]
	v_mfma_f32_16x16x32_bf16 v[98:101], v[164:167], v[228:231], v[98:101]
	v_mfma_f32_16x16x32_bf16 v[94:97], v[208:211], v[228:231], v[94:97]
	v_mfma_f32_16x16x32_bf16 v[82:85], v[164:167], v[236:239], v[82:85]
	v_mfma_f32_16x16x32_bf16 v[78:81], v[208:211], v[236:239], v[78:81]
	v_mfma_f32_16x16x32_bf16 v[66:69], v[164:167], v[244:247], v[66:69]
	v_mfma_f32_16x16x32_bf16 v[62:65], v[208:211], v[244:247], v[62:65]
	v_mfma_f32_16x16x32_bf16 v[114:117], v[204:207], v[224:227], v[114:117]
	v_mfma_f32_16x16x32_bf16 v[110:113], v[216:219], v[224:227], v[110:113]
	v_mfma_f32_16x16x32_bf16 v[98:101], v[204:207], v[232:235], v[98:101]
	v_mfma_f32_16x16x32_bf16 v[94:97], v[216:219], v[232:235], v[94:97]
	v_mfma_f32_16x16x32_bf16 v[82:85], v[204:207], v[240:243], v[82:85]
	v_mfma_f32_16x16x32_bf16 v[78:81], v[216:219], v[240:243], v[78:81]
	v_mfma_f32_16x16x32_bf16 v[66:69], v[204:207], v[248:251], v[66:69]
	v_mfma_f32_16x16x32_bf16 v[62:65], v[216:219], v[248:251], v[62:65]
	s_barrier
	s_add_i32 s53, s53, s17
	v_lshl_add_u64 v[168:169], s[20:21], 0, v[0:1]
	s_mov_b32 m0, s53
	ds_read_b128 v[220:223], v196 offset:16384
	ds_read_b128 v[224:227], v196 offset:17408
	ds_read_b128 v[228:231], v196 offset:18432
	ds_read_b128 v[232:235], v196 offset:19456
	ds_read_b128 v[236:239], v196 offset:20480
	ds_read_b128 v[240:243], v196 offset:21504
	ds_read_b128 v[244:247], v196 offset:22528
	ds_read_b128 v[248:251], v196 offset:23552
	global_load_lds_dwordx4 v[168:169], off
	s_add_i32 m0, s53, 0x2000
	s_add_u32 s56, s20, 0x80000
	v_lshl_add_u64 v[198:199], s[20:21], 0, v[154:155]
	s_addc_u32 s57, s21, 0
	s_add_i32 s53, s54, s17
	global_load_lds_dwordx4 v[198:199], off
	v_lshl_add_u64 v[6:7], s[56:57], 0, v[0:1]
	s_mov_b32 m0, s53
	v_lshl_add_u64 v[200:201], s[22:23], 0, v[150:151]
	global_load_lds_dwordx4 v[6:7], off
	v_lshl_add_u64 v[6:7], s[56:57], 0, v[154:155]
	s_add_i32 m0, s53, 0x2000
	v_lshl_add_u64 v[202:203], s[22:23], 0, v[152:153]
	global_load_lds_dwordx4 v[6:7], off
	s_mov_b32 m0, s38
	s_nop 0
	global_load_lds_dwordx4 v[200:201], off
	s_mov_b32 m0, s39
	s_nop 0
	global_load_lds_dwordx4 v[202:203], off
	s_waitcnt vmcnt(8)
	s_waitcnt lgkmcnt(0)
	s_barrier
	v_mfma_f32_16x16x32_bf16 v[74:77], v[126:129], v[220:223], v[74:77]
	v_mfma_f32_16x16x32_bf16 v[70:73], v[142:145], v[220:223], v[70:73]
	v_mfma_f32_16x16x32_bf16 v[58:61], v[126:129], v[228:231], v[58:61]
	v_mfma_f32_16x16x32_bf16 v[54:57], v[142:145], v[228:231], v[54:57]
	v_mfma_f32_16x16x32_bf16 v[42:45], v[126:129], v[236:239], v[42:45]
	v_mfma_f32_16x16x32_bf16 v[38:41], v[142:145], v[236:239], v[38:41]
	v_mfma_f32_16x16x32_bf16 v[22:25], v[126:129], v[244:247], v[22:25]
	v_mfma_f32_16x16x32_bf16 v[18:21], v[142:145], v[244:247], v[18:21]
	v_mfma_f32_16x16x32_bf16 v[74:77], v[130:133], v[224:227], v[74:77]
	v_mfma_f32_16x16x32_bf16 v[70:73], v[146:149], v[224:227], v[70:73]
	v_mfma_f32_16x16x32_bf16 v[58:61], v[130:133], v[232:235], v[58:61]
	v_mfma_f32_16x16x32_bf16 v[54:57], v[146:149], v[232:235], v[54:57]
	v_mfma_f32_16x16x32_bf16 v[42:45], v[130:133], v[240:243], v[42:45]
	v_mfma_f32_16x16x32_bf16 v[38:41], v[146:149], v[240:243], v[38:41]
	v_mfma_f32_16x16x32_bf16 v[22:25], v[130:133], v[248:251], v[22:25]
	v_mfma_f32_16x16x32_bf16 v[18:21], v[146:149], v[248:251], v[18:21]
	v_mfma_f32_16x16x32_bf16 v[50:53], v[164:167], v[220:223], v[50:53]
	v_mfma_f32_16x16x32_bf16 v[46:49], v[208:211], v[220:223], v[46:49]
	v_mfma_f32_16x16x32_bf16 v[34:37], v[164:167], v[228:231], v[34:37]
	v_mfma_f32_16x16x32_bf16 v[30:33], v[208:211], v[228:231], v[30:33]
	v_mfma_f32_16x16x32_bf16 v[26:29], v[164:167], v[236:239], v[26:29]
	v_mfma_f32_16x16x32_bf16 v[2:5], v[208:211], v[236:239], v[2:5]
	v_mfma_f32_16x16x32_bf16 v[12:15], v[164:167], v[244:247], v[12:15]
	v_mfma_f32_16x16x32_bf16 v[6:9], v[208:211], v[244:247], v[8:11]
	v_mfma_f32_16x16x32_bf16 v[50:53], v[204:207], v[224:227], v[50:53]
	v_mfma_f32_16x16x32_bf16 v[46:49], v[216:219], v[224:227], v[46:49]
	v_mfma_f32_16x16x32_bf16 v[34:37], v[204:207], v[232:235], v[34:37]
	v_mfma_f32_16x16x32_bf16 v[30:33], v[216:219], v[232:235], v[30:33]
	v_mfma_f32_16x16x32_bf16 v[26:29], v[204:207], v[240:243], v[26:29]
	v_mfma_f32_16x16x32_bf16 v[2:5], v[216:219], v[240:243], v[2:5]
	v_mfma_f32_16x16x32_bf16 v[12:15], v[204:207], v[248:251], v[12:15]
	v_mfma_f32_16x16x32_bf16 v[6:9], v[216:219], v[248:251], v[6:9]
	s_barrier
	s_add_i32 s53, 0, 0x18000
	v_add_u32_e32 v10, s53, v170
	s_add_i32 s54, 0, 0x1c000
	ds_read_b128 v[126:129], v10
	ds_read_b128 v[130:133], v10 offset:1024
	ds_read_b128 v[142:145], v10 offset:2048
	ds_read_b128 v[146:149], v10 offset:3072
	v_add_u32_e32 v10, s54, v170
	ds_read_b128 v[164:167], v10
	ds_read_b128 v[204:207], v10 offset:1024
	ds_read_b128 v[208:211], v10 offset:2048
	ds_read_b128 v[216:219], v10 offset:3072
	s_add_u32 s22, s22, 0x80000
	s_addc_u32 s23, s23, 0
	s_mov_b32 m0, s40
	v_lshl_add_u64 v[10:11], s[22:23], 0, v[150:151]
	ds_read_b128 v[220:223], v196 offset:32768
	ds_read_b128 v[224:227], v196 offset:33792
	ds_read_b128 v[228:231], v196 offset:34816
	ds_read_b128 v[232:235], v196 offset:35840
	ds_read_b128 v[236:239], v196 offset:36864
	ds_read_b128 v[240:243], v196 offset:37888
	ds_read_b128 v[244:247], v196 offset:38912
	ds_read_b128 v[248:251], v196 offset:39936
	global_load_lds_dwordx4 v[10:11], off
	v_lshl_add_u64 v[10:11], s[22:23], 0, v[152:153]
	s_mov_b32 m0, s41
	s_nop 0
	global_load_lds_dwordx4 v[10:11], off
	s_waitcnt vmcnt(8)
	s_waitcnt lgkmcnt(0)
	s_barrier
	v_mfma_f32_16x16x32_bf16 v[138:141], v[126:129], v[220:223], v[138:141]
	v_mfma_f32_16x16x32_bf16 v[134:137], v[142:145], v[220:223], v[134:137]
	v_mfma_f32_16x16x32_bf16 v[122:125], v[126:129], v[228:231], v[122:125]
	v_mfma_f32_16x16x32_bf16 v[118:121], v[142:145], v[228:231], v[118:121]
	v_mfma_f32_16x16x32_bf16 v[106:109], v[126:129], v[236:239], v[106:109]
	v_mfma_f32_16x16x32_bf16 v[102:105], v[142:145], v[236:239], v[102:105]
	v_mfma_f32_16x16x32_bf16 v[90:93], v[126:129], v[244:247], v[90:93]
	v_mfma_f32_16x16x32_bf16 v[86:89], v[142:145], v[244:247], v[86:89]
	v_mfma_f32_16x16x32_bf16 v[138:141], v[130:133], v[224:227], v[138:141]
	v_mfma_f32_16x16x32_bf16 v[134:137], v[146:149], v[224:227], v[134:137]
	v_mfma_f32_16x16x32_bf16 v[122:125], v[130:133], v[232:235], v[122:125]
	v_mfma_f32_16x16x32_bf16 v[118:121], v[146:149], v[232:235], v[118:121]
	v_mfma_f32_16x16x32_bf16 v[106:109], v[130:133], v[240:243], v[106:109]
	v_mfma_f32_16x16x32_bf16 v[102:105], v[146:149], v[240:243], v[102:105]
	v_mfma_f32_16x16x32_bf16 v[90:93], v[130:133], v[248:251], v[90:93]
	v_mfma_f32_16x16x32_bf16 v[86:89], v[146:149], v[248:251], v[86:89]
	v_mfma_f32_16x16x32_bf16 v[114:117], v[164:167], v[220:223], v[114:117]
	v_mfma_f32_16x16x32_bf16 v[110:113], v[208:211], v[220:223], v[110:113]
	v_mfma_f32_16x16x32_bf16 v[98:101], v[164:167], v[228:231], v[98:101]
	v_mfma_f32_16x16x32_bf16 v[94:97], v[208:211], v[228:231], v[94:97]
	v_mfma_f32_16x16x32_bf16 v[82:85], v[164:167], v[236:239], v[82:85]
	v_mfma_f32_16x16x32_bf16 v[78:81], v[208:211], v[236:239], v[78:81]
	v_mfma_f32_16x16x32_bf16 v[66:69], v[164:167], v[244:247], v[66:69]
	v_mfma_f32_16x16x32_bf16 v[62:65], v[208:211], v[244:247], v[62:65]
	v_mfma_f32_16x16x32_bf16 v[114:117], v[204:207], v[224:227], v[114:117]
	v_mfma_f32_16x16x32_bf16 v[110:113], v[216:219], v[224:227], v[110:113]
	v_mfma_f32_16x16x32_bf16 v[98:101], v[204:207], v[232:235], v[98:101]
	v_mfma_f32_16x16x32_bf16 v[94:97], v[216:219], v[232:235], v[94:97]
	v_mfma_f32_16x16x32_bf16 v[82:85], v[204:207], v[240:243], v[82:85]
	v_mfma_f32_16x16x32_bf16 v[78:81], v[216:219], v[240:243], v[78:81]
	v_mfma_f32_16x16x32_bf16 v[66:69], v[204:207], v[248:251], v[66:69]
	v_mfma_f32_16x16x32_bf16 v[62:65], v[216:219], v[248:251], v[62:65]
	s_barrier
	s_add_i32 s22, s53, s17
	v_lshl_add_u64 v[10:11], v[168:169], 0, s[36:37]
	s_mov_b32 m0, s22
	ds_read_b128 v[220:223], v196 offset:49152
	ds_read_b128 v[224:227], v196 offset:50176
	ds_read_b128 v[228:231], v196 offset:51200
	ds_read_b128 v[232:235], v196 offset:52224
	ds_read_b128 v[236:239], v196 offset:53248
	ds_read_b128 v[240:243], v196 offset:54272
	ds_read_b128 v[244:247], v196 offset:55296
	ds_read_b128 v[248:251], v196 offset:56320
	global_load_lds_dwordx4 v[10:11], off
	s_add_i32 m0, s22, 0x2000
	s_add_u32 s20, s20, 0x80080
	v_lshl_add_u64 v[10:11], v[198:199], 0, s[36:37]
	s_addc_u32 s21, s21, 0
	s_add_i32 s22, s54, s17
	global_load_lds_dwordx4 v[10:11], off
	v_lshl_add_u64 v[10:11], s[20:21], 0, v[0:1]
	s_mov_b32 m0, s22
	s_nop 0
	global_load_lds_dwordx4 v[10:11], off
	v_lshl_add_u64 v[10:11], s[20:21], 0, v[154:155]
	s_add_i32 m0, s22, 0x2000
	s_nop 0
	global_load_lds_dwordx4 v[10:11], off
	v_lshl_add_u64 v[10:11], v[200:201], 0, s[36:37]
	s_mov_b32 m0, s2
	s_nop 0
	global_load_lds_dwordx4 v[10:11], off
	v_lshl_add_u64 v[10:11], v[202:203], 0, s[36:37]
	s_mov_b32 m0, s3
	s_nop 0
	global_load_lds_dwordx4 v[10:11], off
	s_add_i32 s52, s52, 2
	s_add_u32 s8, s8, 0x100
	s_addc_u32 s9, s9, 0
	s_add_u32 s50, s50, 0x100
	s_addc_u32 s51, s51, 0
	s_cmp_gt_u32 s52, 29
	s_waitcnt vmcnt(8)
	s_waitcnt lgkmcnt(0)
	s_barrier
	v_mfma_f32_16x16x32_bf16 v[74:77], v[126:129], v[220:223], v[74:77]
	v_mfma_f32_16x16x32_bf16 v[70:73], v[142:145], v[220:223], v[70:73]
	v_mfma_f32_16x16x32_bf16 v[58:61], v[126:129], v[228:231], v[58:61]
	v_mfma_f32_16x16x32_bf16 v[54:57], v[142:145], v[228:231], v[54:57]
	v_mfma_f32_16x16x32_bf16 v[42:45], v[126:129], v[236:239], v[42:45]
	v_mfma_f32_16x16x32_bf16 v[38:41], v[142:145], v[236:239], v[38:41]
	v_mfma_f32_16x16x32_bf16 v[22:25], v[126:129], v[244:247], v[22:25]
	v_mfma_f32_16x16x32_bf16 v[18:21], v[142:145], v[244:247], v[18:21]
	v_mfma_f32_16x16x32_bf16 v[74:77], v[130:133], v[224:227], v[74:77]
	v_mfma_f32_16x16x32_bf16 v[70:73], v[146:149], v[224:227], v[70:73]
	v_mfma_f32_16x16x32_bf16 v[58:61], v[130:133], v[232:235], v[58:61]
	v_mfma_f32_16x16x32_bf16 v[54:57], v[146:149], v[232:235], v[54:57]
	v_mfma_f32_16x16x32_bf16 v[42:45], v[130:133], v[240:243], v[42:45]
	v_mfma_f32_16x16x32_bf16 v[38:41], v[146:149], v[240:243], v[38:41]
	v_mfma_f32_16x16x32_bf16 v[22:25], v[130:133], v[248:251], v[22:25]
	v_mfma_f32_16x16x32_bf16 v[18:21], v[146:149], v[248:251], v[18:21]
	v_mfma_f32_16x16x32_bf16 v[50:53], v[164:167], v[220:223], v[50:53]
	v_mfma_f32_16x16x32_bf16 v[46:49], v[208:211], v[220:223], v[46:49]
	v_mfma_f32_16x16x32_bf16 v[34:37], v[164:167], v[228:231], v[34:37]
	v_mfma_f32_16x16x32_bf16 v[30:33], v[208:211], v[228:231], v[30:33]
	v_mfma_f32_16x16x32_bf16 v[26:29], v[164:167], v[236:239], v[26:29]
	v_mfma_f32_16x16x32_bf16 v[2:5], v[208:211], v[236:239], v[2:5]
	v_mfma_f32_16x16x32_bf16 v[10:13], v[164:167], v[244:247], v[12:15]
	v_mfma_f32_16x16x32_bf16 v[6:9], v[208:211], v[244:247], v[6:9]
	v_mfma_f32_16x16x32_bf16 v[50:53], v[204:207], v[224:227], v[50:53]
	v_mfma_f32_16x16x32_bf16 v[46:49], v[216:219], v[224:227], v[46:49]
	v_mfma_f32_16x16x32_bf16 v[34:37], v[204:207], v[232:235], v[34:37]
	v_mfma_f32_16x16x32_bf16 v[30:33], v[216:219], v[232:235], v[30:33]
	v_mfma_f32_16x16x32_bf16 v[26:29], v[204:207], v[240:243], v[26:29]
	v_mfma_f32_16x16x32_bf16 v[2:5], v[216:219], v[240:243], v[2:5]
	v_mfma_f32_16x16x32_bf16 v[12:15], v[204:207], v[248:251], v[10:13]
	v_mfma_f32_16x16x32_bf16 v[8:11], v[216:219], v[248:251], v[6:9]
	s_barrier
	s_cbranch_scc0 .LBB0_878
	s_and_b64 vcc, exec, s[74:75]
	s_cbranch_vccz .LBB0_881
	s_barrier
